# speedup vs baseline: 1.0027x; 1.0003x over previous
; #define WAIT_V(n) asm volatile("s_waitcnt vmcnt(" #n ")" ::: "memory")
; #define WAIT_L(n) asm volatile("s_waitcnt lgkmcnt(" #n ")" ::: "memory")
; #define BAR __builtin_amdgcn_s_barrier()
; #define SCHED __builtin_amdgcn_sched_barrier(0)
; #define STG_A(b, h, kt) stage_half_s(lds0 + ((b) * 2 + (h)) * HT_B, ((h) ? A1 : Ap) + (kt) * BK, off0, off1)
; #define STG_B(b, h, kt) stage_half_s(lds0 + (4 + (b) * 2 + (h)) * HT_B, ((h) ? B1p : Bp) + (kt) * BK, off0, off1)
; #define STG_A(b, h, kt) stage_half_s(lds0 + ((b) * 2 + (h)) * HT_B, ((h) ? A1 : Ap) + (kt) * BK, off0, off1)
; #define STG_B(b, h, kt) stage_half_s(lds0 + (4 + (b) * 2 + (h)) * HT_B, ((h) ? B1p : Bp) + (kt) * BK, off0, off1)
; #define LDA8(b, h) _Pragma("unroll") for (int m = 0; m < 4; ++m) _Pragma("unroll") for (int k = 0; k < 2; ++k) \
;     At[m][k] = *(const bf16x8*)(SA_(shm, b, h) + abase + (m * 2 + k) * 1024)
; #define LDB8(dst, b, h) _Pragma("unroll") for (int n = 0; n < 2; ++n) _Pragma("unroll") for (int k = 0; k < 2; ++k) \
;     dst[n][k] = *(const bf16x8*)(SB_(shm, b, h) + bbase + (n * 2 + k) * 1024)
; #define MMA8(ai, bj, Bx) do { __builtin_amdgcn_s_setprio(1); \
;     _Pragma("unroll") for (int m = 0; m < 4; ++m) _Pragma("unroll") for (int n = 0; n < 2; ++n) _Pragma("unroll") for (int k = 0; k < 2; ++k) \
;       acc[ai][bj][m][n] = __builtin_amdgcn_mfma_f32_16x16x32_bf16(At[m][k], Bx[n][k], acc[ai][bj][m][n], 0, 0, 0); \
;     __builtin_amdgcn_s_setprio(0); } while (0)
; template <bool HS>
; __device__ __forceinline__ void gemm_tile8(const u16* __restrict__ Ap, const u16* __restrict__ Bp, int K,
;                                            f32x4 (&acc)[2][2][4][2], char* shm, const int tid, const float* hsr = nullptr) {
;     ...
;     LDB8(B0, 0, 0); SCHED; LDA8(0, 0); STG_A(1, 1, t + 1);
;     WAIT_L(8); BAR; WAIT_L(0); MMA8(0, 0, B0); BAR; SCHED;
;     LDB8(B1, 0, 1); STG_B(0, 0, t + 2);
;     BAR; WAIT_L(0); MMA8(0, 1, B1); BAR;
;     LDA8(0, 1); STG_A(0, 0, t + 2);
;     BAR; WAIT_L(0); MMA8(1, 0, B0); BAR; SCHED;
;     STG_B(0, 1, t + 2);
;     WAIT_V(6); BAR; MMA8(1, 1, B1); BAR;
.Lffn_in_kinit:
	v_readfirstlane_b32 s20, v130
	v_readfirstlane_b32 s21, v131
	v_readfirstlane_b32 s22, v132
	v_readfirstlane_b32 s23, v133
	s_mov_b32 s16, s5
	s_mov_b32 s17, s6
	s_mov_b32 s18, s12
	s_mov_b32 s19, s13
	s_barrier
	s_barrier
	ds_read_b128 v[146:149], v244
	ds_read_b128 v[150:153], v244 offset:1024
	ds_read_b128 v[154:157], v244 offset:2048
	ds_read_b128 v[158:161], v244 offset:3072
	ds_read_b128 v[162:165], v142
	ds_read_b128 v[166:169], v142 offset:1024
	ds_read_b128 v[170:173], v142 offset:2048
	ds_read_b128 v[174:177], v142 offset:3072
	ds_read_b128 v[180:183], v142 offset:4096
	ds_read_b128 v[184:187], v142 offset:5120
	ds_read_b128 v[188:191], v142 offset:6144
	ds_read_b128 v[192:195], v142 offset:7168
	ds_read_b128 v[196:199], v245
	ds_read_b128 v[200:203], v245 offset:1024
	ds_read_b128 v[204:207], v245 offset:2048
	ds_read_b128 v[208:211], v245 offset:3072
	s_add_i32 s3, s7, 0xc000
	s_mov_b32 m0, s3
	s_add_u32 s0, s18, 0x80
	s_addc_u32 s1, s19, 0
	global_load_lds_dwordx4 v144, s[0:1]
	s_add_i32 s3, s7, 0xe000
	s_mov_b32 m0, s3
	s_nop 0
	global_load_lds_dwordx4 v143, s[0:1]
	s_waitcnt vmcnt(8) lgkmcnt(0)
	s_setprio 1
	s_barrier
	v_mfma_f32_16x16x32_bf16 v[126:129], v[162:165], v[146:149], 0
	v_mfma_f32_16x16x32_bf16 v[122:125], v[162:165], v[154:157], 0
	v_mfma_f32_16x16x32_bf16 v[114:117], v[170:173], v[154:157], 0
	v_mfma_f32_16x16x32_bf16 v[118:121], v[170:173], v[146:149], 0
	v_mfma_f32_16x16x32_bf16 v[110:113], v[180:183], v[146:149], 0
	v_mfma_f32_16x16x32_bf16 v[106:109], v[180:183], v[154:157], 0
	v_mfma_f32_16x16x32_bf16 v[98:101], v[188:191], v[154:157], 0
	v_mfma_f32_16x16x32_bf16 v[102:105], v[188:191], v[146:149], 0
	v_mfma_f32_16x16x32_bf16 v[126:129], v[166:169], v[150:153], v[126:129]
	v_mfma_f32_16x16x32_bf16 v[122:125], v[166:169], v[158:161], v[122:125]
	v_mfma_f32_16x16x32_bf16 v[114:117], v[174:177], v[158:161], v[114:117]
	v_mfma_f32_16x16x32_bf16 v[118:121], v[174:177], v[150:153], v[118:121]
	v_mfma_f32_16x16x32_bf16 v[110:113], v[184:187], v[150:153], v[110:113]
	v_mfma_f32_16x16x32_bf16 v[106:109], v[184:187], v[158:161], v[106:109]
	v_mfma_f32_16x16x32_bf16 v[98:101], v[192:195], v[158:161], v[98:101]
	v_mfma_f32_16x16x32_bf16 v[102:105], v[192:195], v[150:153], v[102:105]
	v_mfma_f32_16x16x32_bf16 v[94:97], v[162:165], v[196:199], 0
	v_mfma_f32_16x16x32_bf16 v[90:93], v[162:165], v[204:207], 0
	v_mfma_f32_16x16x32_bf16 v[82:85], v[170:173], v[204:207], 0
	v_mfma_f32_16x16x32_bf16 v[86:89], v[170:173], v[196:199], 0
	v_mfma_f32_16x16x32_bf16 v[78:81], v[180:183], v[196:199], 0
	v_mfma_f32_16x16x32_bf16 v[74:77], v[180:183], v[204:207], 0
	v_mfma_f32_16x16x32_bf16 v[66:69], v[188:191], v[204:207], 0
	v_mfma_f32_16x16x32_bf16 v[70:73], v[188:191], v[196:199], 0
	v_mfma_f32_16x16x32_bf16 v[94:97], v[166:169], v[200:203], v[94:97]
	v_mfma_f32_16x16x32_bf16 v[90:93], v[166:169], v[208:211], v[90:93]
	v_mfma_f32_16x16x32_bf16 v[82:85], v[174:177], v[208:211], v[82:85]
	v_mfma_f32_16x16x32_bf16 v[86:89], v[174:177], v[200:203], v[86:89]
	v_mfma_f32_16x16x32_bf16 v[78:81], v[184:187], v[200:203], v[78:81]
	v_mfma_f32_16x16x32_bf16 v[74:77], v[184:187], v[208:211], v[74:77]
	v_mfma_f32_16x16x32_bf16 v[66:69], v[192:195], v[208:211], v[66:69]
	v_mfma_f32_16x16x32_bf16 v[70:73], v[192:195], v[200:203], v[70:73]
	s_barrier
	s_setprio 0
	ds_read_b128 v[162:165], v142 offset:16384
	ds_read_b128 v[166:169], v142 offset:17408
	ds_read_b128 v[170:173], v142 offset:18432
	ds_read_b128 v[174:177], v142 offset:19456
	ds_read_b128 v[180:183], v142 offset:20480
	ds_read_b128 v[184:187], v142 offset:21504
	ds_read_b128 v[188:191], v142 offset:22528
	ds_read_b128 v[192:195], v142 offset:23552
	s_add_i32 s3, s7, 0x10000
	s_mov_b32 m0, s3
	s_add_u32 s0, s20, 0x100
	s_addc_u32 s1, s21, 0
	global_load_lds_dwordx4 v144, s[0:1]
	s_add_i32 s3, s7, 0x12000
	s_mov_b32 m0, s3
	s_nop 0
	global_load_lds_dwordx4 v143, s[0:1]
	s_mov_b32 m0, s7
	s_add_u32 s0, s16, 0x100
	s_addc_u32 s1, s17, 0
	global_load_lds_dwordx4 v144, s[0:1]
	s_add_i32 s3, s7, 0x2000
	s_mov_b32 m0, s3
	s_nop 0
	global_load_lds_dwordx4 v143, s[0:1]
	s_add_i32 s3, s7, 0x14000
	s_mov_b32 m0, s3
	s_add_u32 s0, s22, 0x100
	s_addc_u32 s1, s23, 0
	global_load_lds_dwordx4 v144, s[0:1]
	s_add_i32 s3, s7, 0x16000
	s_mov_b32 m0, s3
	s_nop 0
	global_load_lds_dwordx4 v143, s[0:1]
	s_waitcnt vmcnt(8) lgkmcnt(0)
	s_setprio 1
	s_barrier
	v_mfma_f32_16x16x32_bf16 v[62:65], v[162:165], v[146:149], 0
	v_mfma_f32_16x16x32_bf16 v[58:61], v[162:165], v[154:157], 0
	v_mfma_f32_16x16x32_bf16 v[50:53], v[170:173], v[154:157], 0
	v_mfma_f32_16x16x32_bf16 v[54:57], v[170:173], v[146:149], 0
	v_mfma_f32_16x16x32_bf16 v[46:49], v[180:183], v[146:149], 0
	v_mfma_f32_16x16x32_bf16 v[42:45], v[180:183], v[154:157], 0
	v_mfma_f32_16x16x32_bf16 v[34:37], v[188:191], v[154:157], 0
	v_mfma_f32_16x16x32_bf16 v[38:41], v[188:191], v[146:149], 0
	v_mfma_f32_16x16x32_bf16 v[62:65], v[166:169], v[150:153], v[62:65]
	v_mfma_f32_16x16x32_bf16 v[58:61], v[166:169], v[158:161], v[58:61]
	v_mfma_f32_16x16x32_bf16 v[50:53], v[174:177], v[158:161], v[50:53]
	v_mfma_f32_16x16x32_bf16 v[54:57], v[174:177], v[150:153], v[54:57]
	v_mfma_f32_16x16x32_bf16 v[46:49], v[184:187], v[150:153], v[46:49]
	v_mfma_f32_16x16x32_bf16 v[42:45], v[184:187], v[158:161], v[42:45]
	v_mfma_f32_16x16x32_bf16 v[34:37], v[192:195], v[158:161], v[34:37]
	v_mfma_f32_16x16x32_bf16 v[38:41], v[192:195], v[150:153], v[38:41]
	v_mfma_f32_16x16x32_bf16 v[30:33], v[162:165], v[196:199], 0
	v_mfma_f32_16x16x32_bf16 v[26:29], v[162:165], v[204:207], 0
	v_mfma_f32_16x16x32_bf16 v[18:21], v[170:173], v[204:207], 0
	v_mfma_f32_16x16x32_bf16 v[22:25], v[170:173], v[196:199], 0
	v_mfma_f32_16x16x32_bf16 v[14:17], v[180:183], v[196:199], 0
	v_mfma_f32_16x16x32_bf16 v[10:13], v[180:183], v[204:207], 0
	v_mfma_f32_16x16x32_bf16 v[2:5], v[188:191], v[204:207], 0
	v_mfma_f32_16x16x32_bf16 v[6:9], v[188:191], v[196:199], 0
	v_mfma_f32_16x16x32_bf16 v[30:33], v[166:169], v[200:203], v[30:33]
	v_mfma_f32_16x16x32_bf16 v[26:29], v[166:169], v[208:211], v[26:29]
	v_mfma_f32_16x16x32_bf16 v[18:21], v[174:177], v[208:211], v[18:21]
	v_mfma_f32_16x16x32_bf16 v[22:25], v[174:177], v[200:203], v[22:25]
	v_mfma_f32_16x16x32_bf16 v[14:17], v[184:187], v[200:203], v[14:17]
	v_mfma_f32_16x16x32_bf16 v[10:13], v[184:187], v[208:211], v[10:13]
	v_mfma_f32_16x16x32_bf16 v[2:5], v[192:195], v[208:211], v[2:5]
	v_mfma_f32_16x16x32_bf16 v[6:9], v[192:195], v[200:203], v[6:9]
	s_barrier
; #define WAIT_V(n) asm volatile("s_waitcnt vmcnt(" #n ")" ::: "memory")
; #define WAIT_L(n) asm volatile("s_waitcnt lgkmcnt(" #n ")" ::: "memory")
; #define BAR __builtin_amdgcn_s_barrier()
; #define SCHED __builtin_amdgcn_sched_barrier(0)
; #define STG_A(b, h, kt) stage_half_s(lds0 + ((b) * 2 + (h)) * HT_B, ((h) ? A1 : Ap) + (kt) * BK, off0, off1)
; #define STG_B(b, h, kt) stage_half_s(lds0 + (4 + (b) * 2 + (h)) * HT_B, ((h) ? B1p : Bp) + (kt) * BK, off0, off1)
; #define STG_A(b, h, kt) stage_half_s(lds0 + ((b) * 2 + (h)) * HT_B, ((h) ? A1 : Ap) + (kt) * BK, off0, off1)
; #define STG_B(b, h, kt) stage_half_s(lds0 + (4 + (b) * 2 + (h)) * HT_B, ((h) ? B1p : Bp) + (kt) * BK, off0, off1)
; #define LDA8(b, h) _Pragma("unroll") for (int m = 0; m < 4; ++m) _Pragma("unroll") for (int k = 0; k < 2; ++k) \
;     At[m][k] = *(const bf16x8*)(SA_(shm, b, h) + abase + (m * 2 + k) * 1024)
; __device__ __forceinline__ void glds16_s(const void* sbase, unsigned voff, unsigned lds_dst) {
;   unsigned keep;
;   asm volatile("s_mov_b32 %0, m0\n\ts_mov_b32 m0, %3\n\ts_nop 2\n\tglobal_load_lds_dwordx4 %1, %2\n\ts_mov_b32 m0, %0"
;                : "=&s"(keep) : "v"(voff), "s"(sbase), "s"(lds_dst) : "memory");
; }
; __device__ __forceinline__ void stage_half_s(unsigned lds_half, const u16* gsrc, unsigned off0, unsigned off1) {
;   const unsigned long long ga = (unsigned long long)(size_t)gsrc;
;   const unsigned lo = __builtin_amdgcn_readfirstlane((unsigned)ga), hi = __builtin_amdgcn_readfirstlane((unsigned)(ga >> 32));
;   const void* sb = (const void*)(size_t)(((unsigned long long)hi << 32) | lo);
;   const unsigned la = __builtin_amdgcn_readfirstlane(lds_half);
;   glds16_s(sb, off0, la);
;   glds16_s(sb, off1, la + 8192u);
; }
; template <bool HS>
; __device__ __forceinline__ void gemm_tile8(const u16* __restrict__ Ap, const u16* __restrict__ Bp, int K,
;                                            f32x4 (&acc)[2][2][4][2], char* shm, const int tid, const float* hsr = nullptr) {
;     ...
;     LDB8(B0, 1, 0); SCHED; LDA8(1, 0); STG_A(0, 1, t + 2);
;     WAIT_L(8); BAR; WAIT_L(0); MMA8(0, 0, B0); BAR; SCHED;
;     LDB8(B1, 1, 1); STG_B(1, 0, t + 3);
;     BAR; WAIT_L(0); MMA8(0, 1, B1); BAR;
;     LDA8(1, 1); STG_A(1, 0, t + 3);
;     BAR; WAIT_L(0); MMA8(1, 0, B0); BAR; SCHED;
;     STG_B(1, 1, t + 3);
;     WAIT_V(6); BAR; MMA8(1, 1, B1); BAR;
	s_setprio 0
	ds_read_b128 v[146:149], v246
	ds_read_b128 v[150:153], v246 offset:1024
	ds_read_b128 v[154:157], v246 offset:2048
	ds_read_b128 v[158:161], v246 offset:3072
	ds_read_b128 v[162:165], v142 offset:32768
	ds_read_b128 v[166:169], v142 offset:33792
	ds_read_b128 v[170:173], v142 offset:34816
	ds_read_b128 v[174:177], v142 offset:35840
	ds_read_b128 v[180:183], v142 offset:36864
	ds_read_b128 v[184:187], v142 offset:37888
	ds_read_b128 v[188:191], v142 offset:38912
	ds_read_b128 v[192:195], v142 offset:39936
	ds_read_b128 v[196:199], v247
	ds_read_b128 v[200:203], v247 offset:1024
	ds_read_b128 v[204:207], v247 offset:2048
	ds_read_b128 v[208:211], v247 offset:3072
	s_add_i32 s3, s7, 0x4000
	s_mov_b32 m0, s3
	s_add_u32 s0, s18, 0x100
	s_addc_u32 s1, s19, 0
	global_load_lds_dwordx4 v144, s[0:1]
	s_add_i32 s3, s7, 0x6000
	s_mov_b32 m0, s3
	s_nop 0
	global_load_lds_dwordx4 v143, s[0:1]
	s_waitcnt vmcnt(8) lgkmcnt(0)
	s_setprio 1
	s_barrier
	v_mfma_f32_16x16x32_bf16 v[126:129], v[162:165], v[146:149], v[126:129]
	v_mfma_f32_16x16x32_bf16 v[122:125], v[162:165], v[154:157], v[122:125]
	v_mfma_f32_16x16x32_bf16 v[114:117], v[170:173], v[154:157], v[114:117]
	v_mfma_f32_16x16x32_bf16 v[118:121], v[170:173], v[146:149], v[118:121]
	v_mfma_f32_16x16x32_bf16 v[110:113], v[180:183], v[146:149], v[110:113]
	v_mfma_f32_16x16x32_bf16 v[106:109], v[180:183], v[154:157], v[106:109]
	v_mfma_f32_16x16x32_bf16 v[98:101], v[188:191], v[154:157], v[98:101]
	v_mfma_f32_16x16x32_bf16 v[102:105], v[188:191], v[146:149], v[102:105]
	v_mfma_f32_16x16x32_bf16 v[126:129], v[166:169], v[150:153], v[126:129]
	v_mfma_f32_16x16x32_bf16 v[122:125], v[166:169], v[158:161], v[122:125]
	v_mfma_f32_16x16x32_bf16 v[114:117], v[174:177], v[158:161], v[114:117]
	v_mfma_f32_16x16x32_bf16 v[118:121], v[174:177], v[150:153], v[118:121]
	v_mfma_f32_16x16x32_bf16 v[110:113], v[184:187], v[150:153], v[110:113]
	v_mfma_f32_16x16x32_bf16 v[106:109], v[184:187], v[158:161], v[106:109]
	v_mfma_f32_16x16x32_bf16 v[98:101], v[192:195], v[158:161], v[98:101]
	v_mfma_f32_16x16x32_bf16 v[102:105], v[192:195], v[150:153], v[102:105]
	v_mfma_f32_16x16x32_bf16 v[94:97], v[162:165], v[196:199], v[94:97]
	v_mfma_f32_16x16x32_bf16 v[90:93], v[162:165], v[204:207], v[90:93]
	v_mfma_f32_16x16x32_bf16 v[82:85], v[170:173], v[204:207], v[82:85]
	v_mfma_f32_16x16x32_bf16 v[86:89], v[170:173], v[196:199], v[86:89]
	v_mfma_f32_16x16x32_bf16 v[78:81], v[180:183], v[196:199], v[78:81]
	v_mfma_f32_16x16x32_bf16 v[74:77], v[180:183], v[204:207], v[74:77]
	v_mfma_f32_16x16x32_bf16 v[66:69], v[188:191], v[204:207], v[66:69]
	v_mfma_f32_16x16x32_bf16 v[70:73], v[188:191], v[196:199], v[70:73]
	v_mfma_f32_16x16x32_bf16 v[94:97], v[166:169], v[200:203], v[94:97]
	v_mfma_f32_16x16x32_bf16 v[90:93], v[166:169], v[208:211], v[90:93]
	v_mfma_f32_16x16x32_bf16 v[82:85], v[174:177], v[208:211], v[82:85]
	v_mfma_f32_16x16x32_bf16 v[86:89], v[174:177], v[200:203], v[86:89]
	v_mfma_f32_16x16x32_bf16 v[78:81], v[184:187], v[200:203], v[78:81]
	v_mfma_f32_16x16x32_bf16 v[74:77], v[184:187], v[208:211], v[74:77]
	v_mfma_f32_16x16x32_bf16 v[66:69], v[192:195], v[208:211], v[66:69]
	v_mfma_f32_16x16x32_bf16 v[70:73], v[192:195], v[200:203], v[70:73]
	s_barrier
	s_setprio 0
	ds_read_b128 v[162:165], v142 offset:49152
	ds_read_b128 v[166:169], v142 offset:50176
	ds_read_b128 v[170:173], v142 offset:51200
	ds_read_b128 v[174:177], v142 offset:52224
	ds_read_b128 v[180:183], v142 offset:53248
	ds_read_b128 v[184:187], v142 offset:54272
	ds_read_b128 v[188:191], v142 offset:55296
	ds_read_b128 v[192:195], v142 offset:56320
	s_add_i32 s3, s7, 0x18000
	s_mov_b32 m0, s3
	s_add_u32 s0, s20, 0x180
	s_addc_u32 s1, s21, 0
	global_load_lds_dwordx4 v144, s[0:1]
	s_add_i32 s3, s7, 0x1a000
	s_mov_b32 m0, s3
	s_nop 0
	global_load_lds_dwordx4 v143, s[0:1]
	s_add_i32 s3, s7, 0x8000
	s_mov_b32 m0, s3
	s_add_u32 s0, s16, 0x180
	s_addc_u32 s1, s17, 0
	global_load_lds_dwordx4 v144, s[0:1]
	s_add_i32 s3, s7, 0xa000
	s_mov_b32 m0, s3
	s_nop 0
	global_load_lds_dwordx4 v143, s[0:1]
	s_add_i32 s3, s7, 0x1c000
	s_mov_b32 m0, s3
	s_add_u32 s0, s22, 0x180
	s_addc_u32 s1, s23, 0
	global_load_lds_dwordx4 v144, s[0:1]
	s_add_i32 s3, s7, 0x1e000
	s_mov_b32 m0, s3
	s_nop 0
	global_load_lds_dwordx4 v143, s[0:1]
	s_waitcnt vmcnt(8) lgkmcnt(0)
	s_setprio 1
	s_barrier
	v_mfma_f32_16x16x32_bf16 v[62:65], v[162:165], v[146:149], v[62:65]
	v_mfma_f32_16x16x32_bf16 v[58:61], v[162:165], v[154:157], v[58:61]
	v_mfma_f32_16x16x32_bf16 v[50:53], v[170:173], v[154:157], v[50:53]
	v_mfma_f32_16x16x32_bf16 v[54:57], v[170:173], v[146:149], v[54:57]
	v_mfma_f32_16x16x32_bf16 v[46:49], v[180:183], v[146:149], v[46:49]
	v_mfma_f32_16x16x32_bf16 v[42:45], v[180:183], v[154:157], v[42:45]
	v_mfma_f32_16x16x32_bf16 v[34:37], v[188:191], v[154:157], v[34:37]
	v_mfma_f32_16x16x32_bf16 v[38:41], v[188:191], v[146:149], v[38:41]
	v_mfma_f32_16x16x32_bf16 v[62:65], v[166:169], v[150:153], v[62:65]
	v_mfma_f32_16x16x32_bf16 v[58:61], v[166:169], v[158:161], v[58:61]
	v_mfma_f32_16x16x32_bf16 v[50:53], v[174:177], v[158:161], v[50:53]
	v_mfma_f32_16x16x32_bf16 v[54:57], v[174:177], v[150:153], v[54:57]
	v_mfma_f32_16x16x32_bf16 v[46:49], v[184:187], v[150:153], v[46:49]
	v_mfma_f32_16x16x32_bf16 v[42:45], v[184:187], v[158:161], v[42:45]
	v_mfma_f32_16x16x32_bf16 v[34:37], v[192:195], v[158:161], v[34:37]
	v_mfma_f32_16x16x32_bf16 v[38:41], v[192:195], v[150:153], v[38:41]
	v_mfma_f32_16x16x32_bf16 v[30:33], v[162:165], v[196:199], v[30:33]
	v_mfma_f32_16x16x32_bf16 v[26:29], v[162:165], v[204:207], v[26:29]
	v_mfma_f32_16x16x32_bf16 v[18:21], v[170:173], v[204:207], v[18:21]
	v_mfma_f32_16x16x32_bf16 v[22:25], v[170:173], v[196:199], v[22:25]
	v_mfma_f32_16x16x32_bf16 v[14:17], v[180:183], v[196:199], v[14:17]
	v_mfma_f32_16x16x32_bf16 v[10:13], v[180:183], v[204:207], v[10:13]
	v_mfma_f32_16x16x32_bf16 v[2:5], v[188:191], v[204:207], v[2:5]
	v_mfma_f32_16x16x32_bf16 v[6:9], v[188:191], v[196:199], v[6:9]
	v_mfma_f32_16x16x32_bf16 v[30:33], v[166:169], v[200:203], v[30:33]
	v_mfma_f32_16x16x32_bf16 v[26:29], v[166:169], v[208:211], v[26:29]
	v_mfma_f32_16x16x32_bf16 v[18:21], v[174:177], v[208:211], v[18:21]
	v_mfma_f32_16x16x32_bf16 v[22:25], v[174:177], v[200:203], v[22:25]
	v_mfma_f32_16x16x32_bf16 v[14:17], v[184:187], v[200:203], v[14:17]
	v_mfma_f32_16x16x32_bf16 v[10:13], v[184:187], v[208:211], v[10:13]
	v_mfma_f32_16x16x32_bf16 v[2:5], v[192:195], v[208:211], v[2:5]
	v_mfma_f32_16x16x32_bf16 v[6:9], v[192:195], v[200:203], v[6:9]
	s_barrier
	s_setprio 0
	s_add_u32 s16, s16, 0x100
	s_addc_u32 s17, s17, 0
	s_add_u32 s18, s18, 0x100
	s_addc_u32 s19, s19, 0
	s_add_u32 s20, s20, 0x100
	s_addc_u32 s21, s21, 0
	s_add_u32 s22, s22, 0x100
	s_addc_u32 s23, s23, 0
	s_mov_b32 s14, 6
; #define WAIT_V(n) asm volatile("s_waitcnt vmcnt(" #n ")" ::: "memory")
; #define WAIT_L(n) asm volatile("s_waitcnt lgkmcnt(" #n ")" ::: "memory")
; #define BAR __builtin_amdgcn_s_barrier()
; #define SCHED __builtin_amdgcn_sched_barrier(0)
; #define STG_A(b, h, kt) stage_half_s(lds0 + ((b) * 2 + (h)) * HT_B, ((h) ? A1 : Ap) + (kt) * BK, off0, off1)
; #define STG_B(b, h, kt) stage_half_s(lds0 + (4 + (b) * 2 + (h)) * HT_B, ((h) ? B1p : Bp) + (kt) * BK, off0, off1)
; #define STG_A(b, h, kt) stage_half_s(lds0 + ((b) * 2 + (h)) * HT_B, ((h) ? A1 : Ap) + (kt) * BK, off0, off1)
; #define STG_B(b, h, kt) stage_half_s(lds0 + (4 + (b) * 2 + (h)) * HT_B, ((h) ? B1p : Bp) + (kt) * BK, off0, off1)
; #define LDA8(b, h) _Pragma("unroll") for (int m = 0; m < 4; ++m) _Pragma("unroll") for (int k = 0; k < 2; ++k) \
;     At[m][k] = *(const bf16x8*)(SA_(shm, b, h) + abase + (m * 2 + k) * 1024)
; __device__ __forceinline__ void glds16_s(const void* sbase, unsigned voff, unsigned lds_dst) {
;   unsigned keep;
;   asm volatile("s_mov_b32 %0, m0\n\ts_mov_b32 m0, %3\n\ts_nop 2\n\tglobal_load_lds_dwordx4 %1, %2\n\ts_mov_b32 m0, %0"
;                : "=&s"(keep) : "v"(voff), "s"(sbase), "s"(lds_dst) : "memory");
; }
; __device__ __forceinline__ void stage_half_s(unsigned lds_half, const u16* gsrc, unsigned off0, unsigned off1) {
;   const unsigned long long ga = (unsigned long long)(size_t)gsrc;
;   const unsigned lo = __builtin_amdgcn_readfirstlane((unsigned)ga), hi = __builtin_amdgcn_readfirstlane((unsigned)(ga >> 32));
;   const void* sb = (const void*)(size_t)(((unsigned long long)hi << 32) | lo);
;   const unsigned la = __builtin_amdgcn_readfirstlane(lds_half);
;   glds16_s(sb, off0, la);
;   glds16_s(sb, off1, la + 8192u);
; }
; template <bool HS>
; __device__ __forceinline__ void gemm_tile8(const u16* __restrict__ Ap, const u16* __restrict__ Bp, int K,
;                                            f32x4 (&acc)[2][2][4][2], char* shm, const int tid, const float* hsr = nullptr) {
;     ...
;     LDB8(B0, 0, 0); SCHED; LDA8(0, 0); STG_A(1, 1, t + 1);
;     WAIT_L(8); BAR; WAIT_L(0); MMA8(0, 0, B0); BAR; SCHED;
;     LDB8(B1, 0, 1); STG_B(0, 0, t + 2);
;     BAR; WAIT_L(0); MMA8(0, 1, B1); BAR;
;     LDA8(0, 1); STG_A(0, 0, t + 2);
;     BAR; WAIT_L(0); MMA8(1, 0, B0); BAR; SCHED;
;     STG_B(0, 1, t + 2);
;     WAIT_V(6); BAR; MMA8(1, 1, B1); BAR;
.Lk_ffn_in:
	ds_read_b128 v[146:149], v244
	ds_read_b128 v[150:153], v244 offset:1024
	ds_read_b128 v[154:157], v244 offset:2048
	ds_read_b128 v[158:161], v244 offset:3072
	ds_read_b128 v[162:165], v142
	ds_read_b128 v[166:169], v142 offset:1024
	ds_read_b128 v[170:173], v142 offset:2048
	ds_read_b128 v[174:177], v142 offset:3072
	ds_read_b128 v[180:183], v142 offset:4096
	ds_read_b128 v[184:187], v142 offset:5120
	ds_read_b128 v[188:191], v142 offset:6144
	ds_read_b128 v[192:195], v142 offset:7168
	ds_read_b128 v[196:199], v245
	ds_read_b128 v[200:203], v245 offset:1024
	ds_read_b128 v[204:207], v245 offset:2048
	ds_read_b128 v[208:211], v245 offset:3072
	s_add_i32 s3, s7, 0xc000
	s_mov_b32 m0, s3
	s_add_u32 s0, s18, 0x80
	s_addc_u32 s1, s19, 0
	global_load_lds_dwordx4 v144, s[0:1]
	s_add_i32 s3, s7, 0xe000
	s_mov_b32 m0, s3
	s_nop 0
	global_load_lds_dwordx4 v143, s[0:1]
	s_waitcnt vmcnt(8) lgkmcnt(0)
	s_setprio 1
	s_barrier
	v_mfma_f32_16x16x32_bf16 v[126:129], v[162:165], v[146:149], v[126:129]
	v_mfma_f32_16x16x32_bf16 v[122:125], v[162:165], v[154:157], v[122:125]
	v_mfma_f32_16x16x32_bf16 v[114:117], v[170:173], v[154:157], v[114:117]
	v_mfma_f32_16x16x32_bf16 v[118:121], v[170:173], v[146:149], v[118:121]
	v_mfma_f32_16x16x32_bf16 v[110:113], v[180:183], v[146:149], v[110:113]
	v_mfma_f32_16x16x32_bf16 v[106:109], v[180:183], v[154:157], v[106:109]
	v_mfma_f32_16x16x32_bf16 v[98:101], v[188:191], v[154:157], v[98:101]
	v_mfma_f32_16x16x32_bf16 v[102:105], v[188:191], v[146:149], v[102:105]
	v_mfma_f32_16x16x32_bf16 v[126:129], v[166:169], v[150:153], v[126:129]
	v_mfma_f32_16x16x32_bf16 v[122:125], v[166:169], v[158:161], v[122:125]
	v_mfma_f32_16x16x32_bf16 v[114:117], v[174:177], v[158:161], v[114:117]
	v_mfma_f32_16x16x32_bf16 v[118:121], v[174:177], v[150:153], v[118:121]
	v_mfma_f32_16x16x32_bf16 v[110:113], v[184:187], v[150:153], v[110:113]
	v_mfma_f32_16x16x32_bf16 v[106:109], v[184:187], v[158:161], v[106:109]
	v_mfma_f32_16x16x32_bf16 v[98:101], v[192:195], v[158:161], v[98:101]
	v_mfma_f32_16x16x32_bf16 v[102:105], v[192:195], v[150:153], v[102:105]
	v_mfma_f32_16x16x32_bf16 v[94:97], v[162:165], v[196:199], v[94:97]
	v_mfma_f32_16x16x32_bf16 v[90:93], v[162:165], v[204:207], v[90:93]
	v_mfma_f32_16x16x32_bf16 v[82:85], v[170:173], v[204:207], v[82:85]
	v_mfma_f32_16x16x32_bf16 v[86:89], v[170:173], v[196:199], v[86:89]
	v_mfma_f32_16x16x32_bf16 v[78:81], v[180:183], v[196:199], v[78:81]
	v_mfma_f32_16x16x32_bf16 v[74:77], v[180:183], v[204:207], v[74:77]
	v_mfma_f32_16x16x32_bf16 v[66:69], v[188:191], v[204:207], v[66:69]
	v_mfma_f32_16x16x32_bf16 v[70:73], v[188:191], v[196:199], v[70:73]
	v_mfma_f32_16x16x32_bf16 v[94:97], v[166:169], v[200:203], v[94:97]
	v_mfma_f32_16x16x32_bf16 v[90:93], v[166:169], v[208:211], v[90:93]
	v_mfma_f32_16x16x32_bf16 v[82:85], v[174:177], v[208:211], v[82:85]
	v_mfma_f32_16x16x32_bf16 v[86:89], v[174:177], v[200:203], v[86:89]
	v_mfma_f32_16x16x32_bf16 v[78:81], v[184:187], v[200:203], v[78:81]
	v_mfma_f32_16x16x32_bf16 v[74:77], v[184:187], v[208:211], v[74:77]
	v_mfma_f32_16x16x32_bf16 v[66:69], v[192:195], v[208:211], v[66:69]
	v_mfma_f32_16x16x32_bf16 v[70:73], v[192:195], v[200:203], v[70:73]
	s_barrier
	s_setprio 0
	ds_read_b128 v[162:165], v142 offset:16384
	ds_read_b128 v[166:169], v142 offset:17408
	ds_read_b128 v[170:173], v142 offset:18432
	ds_read_b128 v[174:177], v142 offset:19456
	ds_read_b128 v[180:183], v142 offset:20480
	ds_read_b128 v[184:187], v142 offset:21504
	ds_read_b128 v[188:191], v142 offset:22528
	ds_read_b128 v[192:195], v142 offset:23552
	s_add_i32 s3, s7, 0x10000
	s_mov_b32 m0, s3
	s_add_u32 s0, s20, 0x100
	s_addc_u32 s1, s21, 0
	global_load_lds_dwordx4 v144, s[0:1]
	s_add_i32 s3, s7, 0x12000
	s_mov_b32 m0, s3
	s_nop 0
	global_load_lds_dwordx4 v143, s[0:1]
	s_mov_b32 m0, s7
	s_add_u32 s0, s16, 0x100
	s_addc_u32 s1, s17, 0
	global_load_lds_dwordx4 v144, s[0:1]
	s_add_i32 s3, s7, 0x2000
	s_mov_b32 m0, s3
	s_nop 0
	global_load_lds_dwordx4 v143, s[0:1]
	s_add_i32 s3, s7, 0x14000
	s_mov_b32 m0, s3
	s_add_u32 s0, s22, 0x100
	s_addc_u32 s1, s23, 0
	global_load_lds_dwordx4 v144, s[0:1]
	s_add_i32 s3, s7, 0x16000
	s_mov_b32 m0, s3
	s_nop 0
	global_load_lds_dwordx4 v143, s[0:1]
	s_waitcnt vmcnt(8) lgkmcnt(0)
	s_setprio 1
	s_barrier
	v_mfma_f32_16x16x32_bf16 v[62:65], v[162:165], v[146:149], v[62:65]
	v_mfma_f32_16x16x32_bf16 v[58:61], v[162:165], v[154:157], v[58:61]
	v_mfma_f32_16x16x32_bf16 v[50:53], v[170:173], v[154:157], v[50:53]
	v_mfma_f32_16x16x32_bf16 v[54:57], v[170:173], v[146:149], v[54:57]
	v_mfma_f32_16x16x32_bf16 v[46:49], v[180:183], v[146:149], v[46:49]
	v_mfma_f32_16x16x32_bf16 v[42:45], v[180:183], v[154:157], v[42:45]
	v_mfma_f32_16x16x32_bf16 v[34:37], v[188:191], v[154:157], v[34:37]
	v_mfma_f32_16x16x32_bf16 v[38:41], v[188:191], v[146:149], v[38:41]
	v_mfma_f32_16x16x32_bf16 v[62:65], v[166:169], v[150:153], v[62:65]
	v_mfma_f32_16x16x32_bf16 v[58:61], v[166:169], v[158:161], v[58:61]
	v_mfma_f32_16x16x32_bf16 v[50:53], v[174:177], v[158:161], v[50:53]
	v_mfma_f32_16x16x32_bf16 v[54:57], v[174:177], v[150:153], v[54:57]
	v_mfma_f32_16x16x32_bf16 v[46:49], v[184:187], v[150:153], v[46:49]
	v_mfma_f32_16x16x32_bf16 v[42:45], v[184:187], v[158:161], v[42:45]
	v_mfma_f32_16x16x32_bf16 v[34:37], v[192:195], v[158:161], v[34:37]
	v_mfma_f32_16x16x32_bf16 v[38:41], v[192:195], v[150:153], v[38:41]
	v_mfma_f32_16x16x32_bf16 v[30:33], v[162:165], v[196:199], v[30:33]
	v_mfma_f32_16x16x32_bf16 v[26:29], v[162:165], v[204:207], v[26:29]
	v_mfma_f32_16x16x32_bf16 v[18:21], v[170:173], v[204:207], v[18:21]
	v_mfma_f32_16x16x32_bf16 v[22:25], v[170:173], v[196:199], v[22:25]
	v_mfma_f32_16x16x32_bf16 v[14:17], v[180:183], v[196:199], v[14:17]
	v_mfma_f32_16x16x32_bf16 v[10:13], v[180:183], v[204:207], v[10:13]
	v_mfma_f32_16x16x32_bf16 v[2:5], v[188:191], v[204:207], v[2:5]
	v_mfma_f32_16x16x32_bf16 v[6:9], v[188:191], v[196:199], v[6:9]
	v_mfma_f32_16x16x32_bf16 v[30:33], v[166:169], v[200:203], v[30:33]
	v_mfma_f32_16x16x32_bf16 v[26:29], v[166:169], v[208:211], v[26:29]
	v_mfma_f32_16x16x32_bf16 v[18:21], v[174:177], v[208:211], v[18:21]
	v_mfma_f32_16x16x32_bf16 v[22:25], v[174:177], v[200:203], v[22:25]
	v_mfma_f32_16x16x32_bf16 v[14:17], v[184:187], v[200:203], v[14:17]
	v_mfma_f32_16x16x32_bf16 v[10:13], v[184:187], v[208:211], v[10:13]
	v_mfma_f32_16x16x32_bf16 v[2:5], v[192:195], v[208:211], v[2:5]
	v_mfma_f32_16x16x32_bf16 v[6:9], v[192:195], v[200:203], v[6:9]
	s_barrier
; #define WAIT_V(n) asm volatile("s_waitcnt vmcnt(" #n ")" ::: "memory")
; #define WAIT_L(n) asm volatile("s_waitcnt lgkmcnt(" #n ")" ::: "memory")
; #define BAR __builtin_amdgcn_s_barrier()
; #define SCHED __builtin_amdgcn_sched_barrier(0)
; #define STG_A(b, h, kt) stage_half_s(lds0 + ((b) * 2 + (h)) * HT_B, ((h) ? A1 : Ap) + (kt) * BK, off0, off1)
; #define STG_B(b, h, kt) stage_half_s(lds0 + (4 + (b) * 2 + (h)) * HT_B, ((h) ? B1p : Bp) + (kt) * BK, off0, off1)
; #define STG_A(b, h, kt) stage_half_s(lds0 + ((b) * 2 + (h)) * HT_B, ((h) ? A1 : Ap) + (kt) * BK, off0, off1)
; #define STG_B(b, h, kt) stage_half_s(lds0 + (4 + (b) * 2 + (h)) * HT_B, ((h) ? B1p : Bp) + (kt) * BK, off0, off1)
; #define LDA8(b, h) _Pragma("unroll") for (int m = 0; m < 4; ++m) _Pragma("unroll") for (int k = 0; k < 2; ++k) \
;     At[m][k] = *(const bf16x8*)(SA_(shm, b, h) + abase + (m * 2 + k) * 1024)
; __device__ __forceinline__ void glds16_s(const void* sbase, unsigned voff, unsigned lds_dst) {
;   unsigned keep;
;   asm volatile("s_mov_b32 %0, m0\n\ts_mov_b32 m0, %3\n\ts_nop 2\n\tglobal_load_lds_dwordx4 %1, %2\n\ts_mov_b32 m0, %0"
;                : "=&s"(keep) : "v"(voff), "s"(sbase), "s"(lds_dst) : "memory");
; }
; __device__ __forceinline__ void stage_half_s(unsigned lds_half, const u16* gsrc, unsigned off0, unsigned off1) {
;   const unsigned long long ga = (unsigned long long)(size_t)gsrc;
;   const unsigned lo = __builtin_amdgcn_readfirstlane((unsigned)ga), hi = __builtin_amdgcn_readfirstlane((unsigned)(ga >> 32));
;   const void* sb = (const void*)(size_t)(((unsigned long long)hi << 32) | lo);
;   const unsigned la = __builtin_amdgcn_readfirstlane(lds_half);
;   glds16_s(sb, off0, la);
;   glds16_s(sb, off1, la + 8192u);
; }
; template <bool HS>
; __device__ __forceinline__ void gemm_tile8(const u16* __restrict__ Ap, const u16* __restrict__ Bp, int K,
;                                            f32x4 (&acc)[2][2][4][2], char* shm, const int tid, const float* hsr = nullptr) {
;     ...
;     LDB8(B0, 1, 0); SCHED; LDA8(1, 0); STG_A(0, 1, t + 2);
;     WAIT_L(8); BAR; WAIT_L(0); MMA8(0, 0, B0); BAR; SCHED;
;     LDB8(B1, 1, 1); STG_B(1, 0, t + 3);
;     BAR; WAIT_L(0); MMA8(0, 1, B1); BAR;
;     LDA8(1, 1); STG_A(1, 0, t + 3);
;     BAR; WAIT_L(0); MMA8(1, 0, B0); BAR; SCHED;
;     STG_B(1, 1, t + 3);
;     WAIT_V(6); BAR; MMA8(1, 1, B1); BAR;
	s_setprio 0
	ds_read_b128 v[146:149], v246
	ds_read_b128 v[150:153], v246 offset:1024
	ds_read_b128 v[154:157], v246 offset:2048
	ds_read_b128 v[158:161], v246 offset:3072
	ds_read_b128 v[162:165], v142 offset:32768
	ds_read_b128 v[166:169], v142 offset:33792
	ds_read_b128 v[170:173], v142 offset:34816
	ds_read_b128 v[174:177], v142 offset:35840
	ds_read_b128 v[180:183], v142 offset:36864
	ds_read_b128 v[184:187], v142 offset:37888
	ds_read_b128 v[188:191], v142 offset:38912
	ds_read_b128 v[192:195], v142 offset:39936
	ds_read_b128 v[196:199], v247
	ds_read_b128 v[200:203], v247 offset:1024
	ds_read_b128 v[204:207], v247 offset:2048
	ds_read_b128 v[208:211], v247 offset:3072
	s_add_i32 s3, s7, 0x4000
	s_mov_b32 m0, s3
	s_add_u32 s0, s18, 0x100
	s_addc_u32 s1, s19, 0
	global_load_lds_dwordx4 v144, s[0:1]
	s_add_i32 s3, s7, 0x6000
	s_mov_b32 m0, s3
	s_nop 0
	global_load_lds_dwordx4 v143, s[0:1]
	s_waitcnt vmcnt(8) lgkmcnt(0)
	s_setprio 1
	s_barrier
	v_mfma_f32_16x16x32_bf16 v[126:129], v[162:165], v[146:149], v[126:129]
	v_mfma_f32_16x16x32_bf16 v[122:125], v[162:165], v[154:157], v[122:125]
	v_mfma_f32_16x16x32_bf16 v[114:117], v[170:173], v[154:157], v[114:117]
	v_mfma_f32_16x16x32_bf16 v[118:121], v[170:173], v[146:149], v[118:121]
	v_mfma_f32_16x16x32_bf16 v[110:113], v[180:183], v[146:149], v[110:113]
	v_mfma_f32_16x16x32_bf16 v[106:109], v[180:183], v[154:157], v[106:109]
	v_mfma_f32_16x16x32_bf16 v[98:101], v[188:191], v[154:157], v[98:101]
	v_mfma_f32_16x16x32_bf16 v[102:105], v[188:191], v[146:149], v[102:105]
	v_mfma_f32_16x16x32_bf16 v[126:129], v[166:169], v[150:153], v[126:129]
	v_mfma_f32_16x16x32_bf16 v[122:125], v[166:169], v[158:161], v[122:125]
	v_mfma_f32_16x16x32_bf16 v[114:117], v[174:177], v[158:161], v[114:117]
	v_mfma_f32_16x16x32_bf16 v[118:121], v[174:177], v[150:153], v[118:121]
	v_mfma_f32_16x16x32_bf16 v[110:113], v[184:187], v[150:153], v[110:113]
	v_mfma_f32_16x16x32_bf16 v[106:109], v[184:187], v[158:161], v[106:109]
	v_mfma_f32_16x16x32_bf16 v[98:101], v[192:195], v[158:161], v[98:101]
	v_mfma_f32_16x16x32_bf16 v[102:105], v[192:195], v[150:153], v[102:105]
	v_mfma_f32_16x16x32_bf16 v[94:97], v[162:165], v[196:199], v[94:97]
	v_mfma_f32_16x16x32_bf16 v[90:93], v[162:165], v[204:207], v[90:93]
	v_mfma_f32_16x16x32_bf16 v[82:85], v[170:173], v[204:207], v[82:85]
	v_mfma_f32_16x16x32_bf16 v[86:89], v[170:173], v[196:199], v[86:89]
	v_mfma_f32_16x16x32_bf16 v[78:81], v[180:183], v[196:199], v[78:81]
	v_mfma_f32_16x16x32_bf16 v[74:77], v[180:183], v[204:207], v[74:77]
	v_mfma_f32_16x16x32_bf16 v[66:69], v[188:191], v[204:207], v[66:69]
	v_mfma_f32_16x16x32_bf16 v[70:73], v[188:191], v[196:199], v[70:73]
	v_mfma_f32_16x16x32_bf16 v[94:97], v[166:169], v[200:203], v[94:97]
	v_mfma_f32_16x16x32_bf16 v[90:93], v[166:169], v[208:211], v[90:93]
	v_mfma_f32_16x16x32_bf16 v[82:85], v[174:177], v[208:211], v[82:85]
	v_mfma_f32_16x16x32_bf16 v[86:89], v[174:177], v[200:203], v[86:89]
	v_mfma_f32_16x16x32_bf16 v[78:81], v[184:187], v[200:203], v[78:81]
	v_mfma_f32_16x16x32_bf16 v[74:77], v[184:187], v[208:211], v[74:77]
	v_mfma_f32_16x16x32_bf16 v[66:69], v[192:195], v[208:211], v[66:69]
	v_mfma_f32_16x16x32_bf16 v[70:73], v[192:195], v[200:203], v[70:73]
	s_barrier
	s_setprio 0
	ds_read_b128 v[162:165], v142 offset:49152
	ds_read_b128 v[166:169], v142 offset:50176
	ds_read_b128 v[170:173], v142 offset:51200
	ds_read_b128 v[174:177], v142 offset:52224
	ds_read_b128 v[180:183], v142 offset:53248
	ds_read_b128 v[184:187], v142 offset:54272
	ds_read_b128 v[188:191], v142 offset:55296
	ds_read_b128 v[192:195], v142 offset:56320
	s_add_i32 s3, s7, 0x18000
	s_mov_b32 m0, s3
	s_add_u32 s0, s20, 0x180
	s_addc_u32 s1, s21, 0
	global_load_lds_dwordx4 v144, s[0:1]
	s_add_i32 s3, s7, 0x1a000
	s_mov_b32 m0, s3
	s_nop 0
	global_load_lds_dwordx4 v143, s[0:1]
	s_add_i32 s3, s7, 0x8000
	s_mov_b32 m0, s3
	s_add_u32 s0, s16, 0x180
	s_addc_u32 s1, s17, 0
	global_load_lds_dwordx4 v144, s[0:1]
	s_add_i32 s3, s7, 0xa000
	s_mov_b32 m0, s3
	s_nop 0
	global_load_lds_dwordx4 v143, s[0:1]
	s_add_i32 s3, s7, 0x1c000
	s_mov_b32 m0, s3
	s_add_u32 s0, s22, 0x180
	s_addc_u32 s1, s23, 0
	global_load_lds_dwordx4 v144, s[0:1]
	s_add_i32 s3, s7, 0x1e000
	s_mov_b32 m0, s3
	s_nop 0
	global_load_lds_dwordx4 v143, s[0:1]
	s_waitcnt vmcnt(8) lgkmcnt(0)
	s_setprio 1
	s_barrier
	v_mfma_f32_16x16x32_bf16 v[62:65], v[162:165], v[146:149], v[62:65]
	v_mfma_f32_16x16x32_bf16 v[58:61], v[162:165], v[154:157], v[58:61]
	v_mfma_f32_16x16x32_bf16 v[50:53], v[170:173], v[154:157], v[50:53]
	v_mfma_f32_16x16x32_bf16 v[54:57], v[170:173], v[146:149], v[54:57]
	v_mfma_f32_16x16x32_bf16 v[46:49], v[180:183], v[146:149], v[46:49]
	v_mfma_f32_16x16x32_bf16 v[42:45], v[180:183], v[154:157], v[42:45]
	v_mfma_f32_16x16x32_bf16 v[34:37], v[188:191], v[154:157], v[34:37]
	v_mfma_f32_16x16x32_bf16 v[38:41], v[188:191], v[146:149], v[38:41]
	v_mfma_f32_16x16x32_bf16 v[62:65], v[166:169], v[150:153], v[62:65]
	v_mfma_f32_16x16x32_bf16 v[58:61], v[166:169], v[158:161], v[58:61]
	v_mfma_f32_16x16x32_bf16 v[50:53], v[174:177], v[158:161], v[50:53]
	v_mfma_f32_16x16x32_bf16 v[54:57], v[174:177], v[150:153], v[54:57]
	v_mfma_f32_16x16x32_bf16 v[46:49], v[184:187], v[150:153], v[46:49]
	v_mfma_f32_16x16x32_bf16 v[42:45], v[184:187], v[158:161], v[42:45]
	v_mfma_f32_16x16x32_bf16 v[34:37], v[192:195], v[158:161], v[34:37]
	v_mfma_f32_16x16x32_bf16 v[38:41], v[192:195], v[150:153], v[38:41]
	v_mfma_f32_16x16x32_bf16 v[30:33], v[162:165], v[196:199], v[30:33]
	v_mfma_f32_16x16x32_bf16 v[26:29], v[162:165], v[204:207], v[26:29]
	v_mfma_f32_16x16x32_bf16 v[18:21], v[170:173], v[204:207], v[18:21]
	v_mfma_f32_16x16x32_bf16 v[22:25], v[170:173], v[196:199], v[22:25]
	v_mfma_f32_16x16x32_bf16 v[14:17], v[180:183], v[196:199], v[14:17]
	v_mfma_f32_16x16x32_bf16 v[10:13], v[180:183], v[204:207], v[10:13]
	v_mfma_f32_16x16x32_bf16 v[2:5], v[188:191], v[204:207], v[2:5]
	v_mfma_f32_16x16x32_bf16 v[6:9], v[188:191], v[196:199], v[6:9]
	v_mfma_f32_16x16x32_bf16 v[30:33], v[166:169], v[200:203], v[30:33]
	v_mfma_f32_16x16x32_bf16 v[26:29], v[166:169], v[208:211], v[26:29]
	v_mfma_f32_16x16x32_bf16 v[18:21], v[174:177], v[208:211], v[18:21]
	v_mfma_f32_16x16x32_bf16 v[22:25], v[174:177], v[200:203], v[22:25]
	v_mfma_f32_16x16x32_bf16 v[14:17], v[184:187], v[200:203], v[14:17]
	v_mfma_f32_16x16x32_bf16 v[10:13], v[184:187], v[208:211], v[10:13]
	v_mfma_f32_16x16x32_bf16 v[2:5], v[192:195], v[208:211], v[2:5]
	v_mfma_f32_16x16x32_bf16 v[6:9], v[192:195], v[200:203], v[6:9]
	s_barrier
; #define WAIT_V(n) asm volatile("s_waitcnt vmcnt(" #n ")" ::: "memory")
; #define WAIT_L(n) asm volatile("s_waitcnt lgkmcnt(" #n ")" ::: "memory")
; #define BAR __builtin_amdgcn_s_barrier()
; #define STG_A(b, h, kt) stage_half_s(lds0 + ((b) * 2 + (h)) * HT_B, ((h) ? A1 : Ap) + (kt) * BK, off0, off1)
; #define STG_A(b, h, kt) stage_half_s(lds0 + ((b) * 2 + (h)) * HT_B, ((h) ? A1 : Ap) + (kt) * BK, off0, off1)
; #define LDA8(b, h) _Pragma("unroll") for (int m = 0; m < 4; ++m) _Pragma("unroll") for (int k = 0; k < 2; ++k) \
;     At[m][k] = *(const bf16x8*)(SA_(shm, b, h) + abase + (m * 2 + k) * 1024)
; #define LDB8(dst, b, h) _Pragma("unroll") for (int n = 0; n < 2; ++n) _Pragma("unroll") for (int k = 0; k < 2; ++k) \
;     dst[n][k] = *(const bf16x8*)(SB_(shm, b, h) + bbase + (n * 2 + k) * 1024)
; __device__ __forceinline__ void glds16_s(const void* sbase, unsigned voff, unsigned lds_dst) {
;   unsigned keep;
;   asm volatile("s_mov_b32 %0, m0\n\ts_mov_b32 m0, %3\n\ts_nop 2\n\tglobal_load_lds_dwordx4 %1, %2\n\ts_mov_b32 m0, %0"
;                : "=&s"(keep) : "v"(voff), "s"(sbase), "s"(lds_dst) : "memory");
; }
; __device__ __forceinline__ void stage_half_s(unsigned lds_half, const u16* gsrc, unsigned off0, unsigned off1) {
;   const unsigned long long ga = (unsigned long long)(size_t)gsrc;
;   const unsigned lo = __builtin_amdgcn_readfirstlane((unsigned)ga), hi = __builtin_amdgcn_readfirstlane((unsigned)(ga >> 32));
;   const void* sb = (const void*)(size_t)(((unsigned long long)hi << 32) | lo);
;   const unsigned la = __builtin_amdgcn_readfirstlane(lds_half);
;   glds16_s(sb, off0, la);
;   glds16_s(sb, off1, la + 8192u);
; }
; template <bool HS>
; __device__ __forceinline__ void gemm_tile8(const u16* __restrict__ Ap, const u16* __restrict__ Bp, int K,
;                                            f32x4 (&acc)[2][2][4][2], char* shm, const int tid, const float* hsr = nullptr) {
;     ...
;   }
;   { LDB8(B0, 0, 0); LDA8(0, 0); STG_A(1, 1, nt - 1);
;     BAR; WAIT_L(0); MMA8(0, 0, B0); BAR;
;     LDB8(B1, 0, 1); BAR; WAIT_L(0); MMA8(0, 1, B1); BAR;
;     LDA8(0, 1); WAIT_V(4); BAR; WAIT_L(0); MMA8(1, 0, B0); MMA8(1, 1, B1); BAR; }
;   { LDB8(B0, 1, 0); LDA8(1, 0); WAIT_V(2); BAR; WAIT_L(0); MMA8(0, 0, B0); BAR;
	s_setprio 0
	s_add_u32 s16, s16, 0x100
	s_addc_u32 s17, s17, 0
	s_add_u32 s18, s18, 0x100
	s_addc_u32 s19, s19, 0
	s_add_u32 s20, s20, 0x100
	s_addc_u32 s21, s21, 0
	s_add_u32 s22, s22, 0x100
	s_addc_u32 s23, s23, 0
	s_sub_i32 s14, s14, 1
	s_cmp_lg_u32 s14, 0
	s_cbranch_scc1 .Lk_ffn_in
	ds_read_b128 v[146:149], v244
	ds_read_b128 v[150:153], v244 offset:1024
	ds_read_b128 v[154:157], v244 offset:2048
	ds_read_b128 v[158:161], v244 offset:3072
	ds_read_b128 v[162:165], v142
	ds_read_b128 v[166:169], v142 offset:1024
	ds_read_b128 v[170:173], v142 offset:2048
	ds_read_b128 v[174:177], v142 offset:3072
	ds_read_b128 v[180:183], v142 offset:4096
	ds_read_b128 v[184:187], v142 offset:5120
	ds_read_b128 v[188:191], v142 offset:6144
	ds_read_b128 v[192:195], v142 offset:7168
	ds_read_b128 v[196:199], v245
	ds_read_b128 v[200:203], v245 offset:1024
	ds_read_b128 v[204:207], v245 offset:2048
	ds_read_b128 v[208:211], v245 offset:3072
	s_add_i32 s3, s7, 0xc000
	s_mov_b32 m0, s3
	s_add_u32 s0, s18, 0x80
	s_addc_u32 s1, s19, 0
	global_load_lds_dwordx4 v144, s[0:1]
	s_add_i32 s3, s7, 0xe000
	s_mov_b32 m0, s3
	s_nop 0
	global_load_lds_dwordx4 v143, s[0:1]
	s_waitcnt vmcnt(8) lgkmcnt(0)
	s_setprio 1
	s_barrier
	v_mfma_f32_16x16x32_bf16 v[126:129], v[162:165], v[146:149], v[126:129]
	v_mfma_f32_16x16x32_bf16 v[122:125], v[162:165], v[154:157], v[122:125]
	v_mfma_f32_16x16x32_bf16 v[114:117], v[170:173], v[154:157], v[114:117]
	v_mfma_f32_16x16x32_bf16 v[118:121], v[170:173], v[146:149], v[118:121]
	v_mfma_f32_16x16x32_bf16 v[110:113], v[180:183], v[146:149], v[110:113]
	v_mfma_f32_16x16x32_bf16 v[106:109], v[180:183], v[154:157], v[106:109]
	v_mfma_f32_16x16x32_bf16 v[98:101], v[188:191], v[154:157], v[98:101]
	v_mfma_f32_16x16x32_bf16 v[102:105], v[188:191], v[146:149], v[102:105]
	v_mfma_f32_16x16x32_bf16 v[126:129], v[166:169], v[150:153], v[126:129]
	v_mfma_f32_16x16x32_bf16 v[122:125], v[166:169], v[158:161], v[122:125]
	v_mfma_f32_16x16x32_bf16 v[114:117], v[174:177], v[158:161], v[114:117]
	v_mfma_f32_16x16x32_bf16 v[118:121], v[174:177], v[150:153], v[118:121]
	v_mfma_f32_16x16x32_bf16 v[110:113], v[184:187], v[150:153], v[110:113]
	v_mfma_f32_16x16x32_bf16 v[106:109], v[184:187], v[158:161], v[106:109]
	v_mfma_f32_16x16x32_bf16 v[98:101], v[192:195], v[158:161], v[98:101]
	v_mfma_f32_16x16x32_bf16 v[102:105], v[192:195], v[150:153], v[102:105]
	v_mfma_f32_16x16x32_bf16 v[94:97], v[162:165], v[196:199], v[94:97]
	v_mfma_f32_16x16x32_bf16 v[90:93], v[162:165], v[204:207], v[90:93]
	v_mfma_f32_16x16x32_bf16 v[82:85], v[170:173], v[204:207], v[82:85]
	v_mfma_f32_16x16x32_bf16 v[86:89], v[170:173], v[196:199], v[86:89]
	v_mfma_f32_16x16x32_bf16 v[78:81], v[180:183], v[196:199], v[78:81]
	v_mfma_f32_16x16x32_bf16 v[74:77], v[180:183], v[204:207], v[74:77]
	v_mfma_f32_16x16x32_bf16 v[66:69], v[188:191], v[204:207], v[66:69]
	v_mfma_f32_16x16x32_bf16 v[70:73], v[188:191], v[196:199], v[70:73]
	v_mfma_f32_16x16x32_bf16 v[94:97], v[166:169], v[200:203], v[94:97]
	v_mfma_f32_16x16x32_bf16 v[90:93], v[166:169], v[208:211], v[90:93]
	v_mfma_f32_16x16x32_bf16 v[82:85], v[174:177], v[208:211], v[82:85]
	v_mfma_f32_16x16x32_bf16 v[86:89], v[174:177], v[200:203], v[86:89]
	v_mfma_f32_16x16x32_bf16 v[78:81], v[184:187], v[200:203], v[78:81]
	v_mfma_f32_16x16x32_bf16 v[74:77], v[184:187], v[208:211], v[74:77]
	v_mfma_f32_16x16x32_bf16 v[66:69], v[192:195], v[208:211], v[66:69]
	v_mfma_f32_16x16x32_bf16 v[70:73], v[192:195], v[200:203], v[70:73]
	s_barrier
	s_setprio 0
	ds_read_b128 v[162:165], v142 offset:16384
	ds_read_b128 v[166:169], v142 offset:17408
	ds_read_b128 v[170:173], v142 offset:18432
	ds_read_b128 v[174:177], v142 offset:19456
	ds_read_b128 v[180:183], v142 offset:20480
	ds_read_b128 v[184:187], v142 offset:21504
	ds_read_b128 v[188:191], v142 offset:22528
	ds_read_b128 v[192:195], v142 offset:23552
	s_waitcnt vmcnt(2) lgkmcnt(0)
	s_setprio 1
	s_barrier
	v_mfma_f32_16x16x32_bf16 v[62:65], v[162:165], v[146:149], v[62:65]
	v_mfma_f32_16x16x32_bf16 v[58:61], v[162:165], v[154:157], v[58:61]
	v_mfma_f32_16x16x32_bf16 v[50:53], v[170:173], v[154:157], v[50:53]
	v_mfma_f32_16x16x32_bf16 v[54:57], v[170:173], v[146:149], v[54:57]
	v_mfma_f32_16x16x32_bf16 v[46:49], v[180:183], v[146:149], v[46:49]
	v_mfma_f32_16x16x32_bf16 v[42:45], v[180:183], v[154:157], v[42:45]
	v_mfma_f32_16x16x32_bf16 v[34:37], v[188:191], v[154:157], v[34:37]
	v_mfma_f32_16x16x32_bf16 v[38:41], v[188:191], v[146:149], v[38:41]
	v_mfma_f32_16x16x32_bf16 v[62:65], v[166:169], v[150:153], v[62:65]
	v_mfma_f32_16x16x32_bf16 v[58:61], v[166:169], v[158:161], v[58:61]
	v_mfma_f32_16x16x32_bf16 v[50:53], v[174:177], v[158:161], v[50:53]
	v_mfma_f32_16x16x32_bf16 v[54:57], v[174:177], v[150:153], v[54:57]
	v_mfma_f32_16x16x32_bf16 v[46:49], v[184:187], v[150:153], v[46:49]
	v_mfma_f32_16x16x32_bf16 v[42:45], v[184:187], v[158:161], v[42:45]
	v_mfma_f32_16x16x32_bf16 v[34:37], v[192:195], v[158:161], v[34:37]
	v_mfma_f32_16x16x32_bf16 v[38:41], v[192:195], v[150:153], v[38:41]
	v_mfma_f32_16x16x32_bf16 v[30:33], v[162:165], v[196:199], v[30:33]
	v_mfma_f32_16x16x32_bf16 v[26:29], v[162:165], v[204:207], v[26:29]
	v_mfma_f32_16x16x32_bf16 v[18:21], v[170:173], v[204:207], v[18:21]
	v_mfma_f32_16x16x32_bf16 v[22:25], v[170:173], v[196:199], v[22:25]
	v_mfma_f32_16x16x32_bf16 v[14:17], v[180:183], v[196:199], v[14:17]
	v_mfma_f32_16x16x32_bf16 v[10:13], v[180:183], v[204:207], v[10:13]
	v_mfma_f32_16x16x32_bf16 v[2:5], v[188:191], v[204:207], v[2:5]
	v_mfma_f32_16x16x32_bf16 v[6:9], v[188:191], v[196:199], v[6:9]
	v_mfma_f32_16x16x32_bf16 v[30:33], v[166:169], v[200:203], v[30:33]
	v_mfma_f32_16x16x32_bf16 v[26:29], v[166:169], v[208:211], v[26:29]
	v_mfma_f32_16x16x32_bf16 v[18:21], v[174:177], v[208:211], v[18:21]
	v_mfma_f32_16x16x32_bf16 v[22:25], v[174:177], v[200:203], v[22:25]
	v_mfma_f32_16x16x32_bf16 v[14:17], v[184:187], v[200:203], v[14:17]
	v_mfma_f32_16x16x32_bf16 v[10:13], v[184:187], v[208:211], v[10:13]
	v_mfma_f32_16x16x32_bf16 v[2:5], v[192:195], v[208:211], v[2:5]
	v_mfma_f32_16x16x32_bf16 v[6:9], v[192:195], v[200:203], v[6:9]
	s_barrier
; #define WAIT_V(n) asm volatile("s_waitcnt vmcnt(" #n ")" ::: "memory")
; #define WAIT_L(n) asm volatile("s_waitcnt lgkmcnt(" #n ")" ::: "memory")
; #define BAR __builtin_amdgcn_s_barrier()
; #define LDA8(b, h) _Pragma("unroll") for (int m = 0; m < 4; ++m) _Pragma("unroll") for (int k = 0; k < 2; ++k) \
;     At[m][k] = *(const bf16x8*)(SA_(shm, b, h) + abase + (m * 2 + k) * 1024)
; #define LDB8(dst, b, h) _Pragma("unroll") for (int n = 0; n < 2; ++n) _Pragma("unroll") for (int k = 0; k < 2; ++k) \
;     dst[n][k] = *(const bf16x8*)(SB_(shm, b, h) + bbase + (n * 2 + k) * 1024)
; #define MMA8(ai, bj, Bx) do { __builtin_amdgcn_s_setprio(1); \
;     _Pragma("unroll") for (int m = 0; m < 4; ++m) _Pragma("unroll") for (int n = 0; n < 2; ++n) _Pragma("unroll") for (int k = 0; k < 2; ++k) \
;       acc[ai][bj][m][n] = __builtin_amdgcn_mfma_f32_16x16x32_bf16(At[m][k], Bx[n][k], acc[ai][bj][m][n], 0, 0, 0); \
;     __builtin_amdgcn_s_setprio(0); } while (0)
; template <bool HS>
; __device__ __forceinline__ void gemm_tile8(const u16* __restrict__ Ap, const u16* __restrict__ Bp, int K,
;                                            f32x4 (&acc)[2][2][4][2], char* shm, const int tid, const float* hsr = nullptr) {
;     ...
;   { LDB8(B0, 1, 0); LDA8(1, 0); WAIT_V(2); BAR; WAIT_L(0); MMA8(0, 0, B0); BAR;
;     LDB8(B1, 1, 1); WAIT_V(0); BAR; WAIT_L(0); MMA8(0, 1, B1); BAR;
;     LDA8(1, 1); BAR; WAIT_L(0); MMA8(1, 0, B0); MMA8(1, 1, B1); BAR; }
;   if (wr == 0) BAR;
	s_setprio 0
	ds_read_b128 v[146:149], v246
	ds_read_b128 v[150:153], v246 offset:1024
	ds_read_b128 v[154:157], v246 offset:2048
	ds_read_b128 v[158:161], v246 offset:3072
	ds_read_b128 v[162:165], v142 offset:32768
	ds_read_b128 v[166:169], v142 offset:33792
	ds_read_b128 v[170:173], v142 offset:34816
	ds_read_b128 v[174:177], v142 offset:35840
	ds_read_b128 v[180:183], v142 offset:36864
	ds_read_b128 v[184:187], v142 offset:37888
	ds_read_b128 v[188:191], v142 offset:38912
	ds_read_b128 v[192:195], v142 offset:39936
	ds_read_b128 v[196:199], v247
	ds_read_b128 v[200:203], v247 offset:1024
	ds_read_b128 v[204:207], v247 offset:2048
	ds_read_b128 v[208:211], v247 offset:3072
	s_waitcnt vmcnt(0) lgkmcnt(0)
	s_setprio 1
	s_barrier
	v_mfma_f32_16x16x32_bf16 v[126:129], v[162:165], v[146:149], v[126:129]
	v_mfma_f32_16x16x32_bf16 v[122:125], v[162:165], v[154:157], v[122:125]
	v_mfma_f32_16x16x32_bf16 v[114:117], v[170:173], v[154:157], v[114:117]
	v_mfma_f32_16x16x32_bf16 v[118:121], v[170:173], v[146:149], v[118:121]
	v_mfma_f32_16x16x32_bf16 v[110:113], v[180:183], v[146:149], v[110:113]
	v_mfma_f32_16x16x32_bf16 v[106:109], v[180:183], v[154:157], v[106:109]
	v_mfma_f32_16x16x32_bf16 v[98:101], v[188:191], v[154:157], v[98:101]
	v_mfma_f32_16x16x32_bf16 v[102:105], v[188:191], v[146:149], v[102:105]
	v_mfma_f32_16x16x32_bf16 v[126:129], v[166:169], v[150:153], v[126:129]
	v_mfma_f32_16x16x32_bf16 v[122:125], v[166:169], v[158:161], v[122:125]
	v_mfma_f32_16x16x32_bf16 v[114:117], v[174:177], v[158:161], v[114:117]
	v_mfma_f32_16x16x32_bf16 v[118:121], v[174:177], v[150:153], v[118:121]
	v_mfma_f32_16x16x32_bf16 v[110:113], v[184:187], v[150:153], v[110:113]
	v_mfma_f32_16x16x32_bf16 v[106:109], v[184:187], v[158:161], v[106:109]
	v_mfma_f32_16x16x32_bf16 v[98:101], v[192:195], v[158:161], v[98:101]
	v_mfma_f32_16x16x32_bf16 v[102:105], v[192:195], v[150:153], v[102:105]
	v_mfma_f32_16x16x32_bf16 v[94:97], v[162:165], v[196:199], v[94:97]
	v_mfma_f32_16x16x32_bf16 v[90:93], v[162:165], v[204:207], v[90:93]
	v_mfma_f32_16x16x32_bf16 v[82:85], v[170:173], v[204:207], v[82:85]
	v_mfma_f32_16x16x32_bf16 v[86:89], v[170:173], v[196:199], v[86:89]
	v_mfma_f32_16x16x32_bf16 v[78:81], v[180:183], v[196:199], v[78:81]
	v_mfma_f32_16x16x32_bf16 v[74:77], v[180:183], v[204:207], v[74:77]
	v_mfma_f32_16x16x32_bf16 v[66:69], v[188:191], v[204:207], v[66:69]
	v_mfma_f32_16x16x32_bf16 v[70:73], v[188:191], v[196:199], v[70:73]
	v_mfma_f32_16x16x32_bf16 v[94:97], v[166:169], v[200:203], v[94:97]
	v_mfma_f32_16x16x32_bf16 v[90:93], v[166:169], v[208:211], v[90:93]
	v_mfma_f32_16x16x32_bf16 v[82:85], v[174:177], v[208:211], v[82:85]
	v_mfma_f32_16x16x32_bf16 v[86:89], v[174:177], v[200:203], v[86:89]
	v_mfma_f32_16x16x32_bf16 v[78:81], v[184:187], v[200:203], v[78:81]
	v_mfma_f32_16x16x32_bf16 v[74:77], v[184:187], v[208:211], v[74:77]
	v_mfma_f32_16x16x32_bf16 v[66:69], v[192:195], v[208:211], v[66:69]
	v_mfma_f32_16x16x32_bf16 v[70:73], v[192:195], v[200:203], v[70:73]
	s_barrier
	s_setprio 0
	ds_read_b128 v[162:165], v142 offset:49152
	ds_read_b128 v[166:169], v142 offset:50176
	ds_read_b128 v[170:173], v142 offset:51200
	ds_read_b128 v[174:177], v142 offset:52224
	ds_read_b128 v[180:183], v142 offset:53248
	ds_read_b128 v[184:187], v142 offset:54272
	ds_read_b128 v[188:191], v142 offset:55296
	ds_read_b128 v[192:195], v142 offset:56320
	s_waitcnt lgkmcnt(0)
	s_setprio 1
	s_barrier
	v_mfma_f32_16x16x32_bf16 v[62:65], v[162:165], v[146:149], v[62:65]
	v_mfma_f32_16x16x32_bf16 v[58:61], v[162:165], v[154:157], v[58:61]
	v_mfma_f32_16x16x32_bf16 v[50:53], v[170:173], v[154:157], v[50:53]
	v_mfma_f32_16x16x32_bf16 v[54:57], v[170:173], v[146:149], v[54:57]
	v_mfma_f32_16x16x32_bf16 v[46:49], v[180:183], v[146:149], v[46:49]
	v_mfma_f32_16x16x32_bf16 v[42:45], v[180:183], v[154:157], v[42:45]
	v_mfma_f32_16x16x32_bf16 v[34:37], v[188:191], v[154:157], v[34:37]
	v_mfma_f32_16x16x32_bf16 v[38:41], v[188:191], v[146:149], v[38:41]
	v_mfma_f32_16x16x32_bf16 v[62:65], v[166:169], v[150:153], v[62:65]
	v_mfma_f32_16x16x32_bf16 v[58:61], v[166:169], v[158:161], v[58:61]
	v_mfma_f32_16x16x32_bf16 v[50:53], v[174:177], v[158:161], v[50:53]
	v_mfma_f32_16x16x32_bf16 v[54:57], v[174:177], v[150:153], v[54:57]
	v_mfma_f32_16x16x32_bf16 v[46:49], v[184:187], v[150:153], v[46:49]
	v_mfma_f32_16x16x32_bf16 v[42:45], v[184:187], v[158:161], v[42:45]
	v_mfma_f32_16x16x32_bf16 v[34:37], v[192:195], v[158:161], v[34:37]
	v_mfma_f32_16x16x32_bf16 v[38:41], v[192:195], v[150:153], v[38:41]
	v_mfma_f32_16x16x32_bf16 v[30:33], v[162:165], v[196:199], v[30:33]
	v_mfma_f32_16x16x32_bf16 v[26:29], v[162:165], v[204:207], v[26:29]
	v_mfma_f32_16x16x32_bf16 v[18:21], v[170:173], v[204:207], v[18:21]
	v_mfma_f32_16x16x32_bf16 v[22:25], v[170:173], v[196:199], v[22:25]
	v_mfma_f32_16x16x32_bf16 v[14:17], v[180:183], v[196:199], v[14:17]
	v_mfma_f32_16x16x32_bf16 v[10:13], v[180:183], v[204:207], v[10:13]
	v_mfma_f32_16x16x32_bf16 v[2:5], v[188:191], v[204:207], v[2:5]
	v_mfma_f32_16x16x32_bf16 v[6:9], v[188:191], v[196:199], v[6:9]
	v_mfma_f32_16x16x32_bf16 v[30:33], v[166:169], v[200:203], v[30:33]
	v_mfma_f32_16x16x32_bf16 v[26:29], v[166:169], v[208:211], v[26:29]
	v_mfma_f32_16x16x32_bf16 v[18:21], v[174:177], v[208:211], v[18:21]
	v_mfma_f32_16x16x32_bf16 v[22:25], v[174:177], v[200:203], v[22:25]
	v_mfma_f32_16x16x32_bf16 v[14:17], v[184:187], v[200:203], v[14:17]
	v_mfma_f32_16x16x32_bf16 v[10:13], v[184:187], v[208:211], v[10:13]
	v_mfma_f32_16x16x32_bf16 v[2:5], v[192:195], v[208:211], v[2:5]
	v_mfma_f32_16x16x32_bf16 v[6:9], v[192:195], v[200:203], v[6:9]
	s_setprio 0
	s_movk_i32 s0, 0x100
	v_cmp_gt_u32_e32 vcc, s0, v0
	s_barrier
	s_and_saveexec_b64 s[0:1], vcc
	s_cbranch_execz .LBB0_862
	s_barrier
